# grid barrier: acquire-side buffer_inv sc1 issued before the flag poll instead of after it (no loads of this CU in between), so the L1 invalidate overlaps the wait
# baseline (speedup 1.0000x reference)
; DI void grid_barrier(unsigned* bar, unsigned gen) {
;     ...
;     while (__hip_atomic_load(bar + 64 * (17 + grp), __ATOMIC_RELAXED, __HIP_MEMORY_SCOPE_AGENT) < gen) __builtin_amdgcn_s_sleep(4);
;     __builtin_amdgcn_fence(__ATOMIC_ACQUIRE, "agent");
.LBB0_25:
	s_or_b64 exec, exec, s[14:15]
	buffer_inv sc1
	global_load_dword v0, v170, s[10:11] offset:256 sc1
	s_add_u32 s10, s10, 0x1100
	s_addc_u32 s11, s11, 0
	s_waitcnt vmcnt(0)
	v_cmp_le_u32_e32 vcc, s20, v0
	s_cbranch_vccnz .LBB0_27

; DI void grid_barrier(unsigned* bar, unsigned gen) {
;     ...
;     while (__hip_atomic_load(bar + 64 * (17 + grp), __ATOMIC_RELAXED, __HIP_MEMORY_SCOPE_AGENT) < gen) __builtin_amdgcn_s_sleep(4);
;     __builtin_amdgcn_fence(__ATOMIC_ACQUIRE, "agent");
;   }
;   __syncthreads();
.LBB0_27:
.LBB0_28:
	s_or_b64 exec, exec, s[8:9]
	v_readlane_b32 s10, v254, 46
	v_readlane_b32 s11, v254, 47
	s_barrier
